# weight conversion items: the 16 transposed LDS reads issued together with a single wait
# baseline (speedup 1.0000x reference)
; #define LAS __attribute__((address_space(3)))
; __device__ __forceinline__ unsigned cvt_pk_bf16(float lo, float hi) { unsigned r; asm volatile("v_cvt_pk_bf16_f32 %0, %1, %2" : "=v"(r) : "v"(lo), "v"(hi)); return r; }
; #define LDS_WAIT() asm volatile("s_waitcnt lgkmcnt(0)" ::: "memory")
; #pragma unroll 8
;     for (int i = 0; i < 32; ++i) { const int kk = 2 * i + (lane >> 5); scr[kk * 33 + (lane & 31)] = __builtin_nontemporal_load(W + (size_t)(k0 + kk) * N + n0 + (lane & 31)); }
;     LDS_WAIT(); asm volatile("" ::: "memory");
;     const int c = lane & 7;
; #pragma unroll
;     for (int j = 0; j < 4; ++j) { const int n = (lane >> 3) + 8 * j; const LAS float* s = scr + (8 * c) * 33 + n;
;         u32x4 o; o.x = cvt_pk_bf16(s[0 * 33] * wscale, s[1 * 33] * wscale); o.y = cvt_pk_bf16(s[2 * 33] * wscale, s[3 * 33] * wscale); o.z = cvt_pk_bf16(s[4 * 33] * wscale, s[5 * 33] * wscale); o.w = cvt_pk_bf16(s[6 * 33] * wscale, s[7 * 33] * wscale);
;         __builtin_nontemporal_store(o, (u32x4*)(WT + (size_t)(drow0 + n0 + n) * K + k0 + 8 * c)); }
;     LDS_WAIT(); asm volatile("" ::: "memory");
; __device__ __forceinline__ void prologue_a(const Args& a, LAS unsigned char* lds, int tid, int G) {
;     ...
;                 r -= 9728; const int kb = r / 32, nb = r % 32;
;                 transpose_item(a.in[I_WOUT] + (size_t)l * DM * DM, DM, kb * 64, nb * 32, (bf16_t*)(ws + WS_WOUT) + (size_t)l * DM * DM, DM, 0, scr, lane);
.LBB0_34:
	v_lshl_add_u64 v[110:111], v[32:33], 0, s[20:21]
	global_load_dword v78, v[110:111], off nt
	v_lshl_add_u64 v[112:113], v[30:31], 0, s[20:21]
	global_load_dword v79, v[112:113], off nt
	v_lshl_add_u64 v[114:115], v[28:29], 0, s[20:21]
	global_load_dword v80, v[114:115], off nt
	v_lshl_add_u64 v[116:117], v[26:27], 0, s[20:21]
	global_load_dword v81, v[116:117], off nt
	v_lshl_add_u64 v[110:111], v[24:25], 0, s[20:21]
	global_load_dword v82, v[110:111], off nt
	v_lshl_add_u64 v[112:113], v[22:23], 0, s[20:21]
	global_load_dword v83, v[112:113], off nt
	v_lshl_add_u64 v[114:115], v[20:21], 0, s[20:21]
	global_load_dword v84, v[114:115], off nt
	v_lshl_add_u64 v[116:117], v[18:19], 0, s[20:21]
	global_load_dword v85, v[116:117], off nt
	s_add_u32 s20, s20, 0x10000
	s_addc_u32 s21, s21, 0
	v_lshl_add_u64 v[110:111], v[32:33], 0, s[20:21]
	global_load_dword v86, v[110:111], off nt
	v_lshl_add_u64 v[112:113], v[30:31], 0, s[20:21]
	global_load_dword v87, v[112:113], off nt
	v_lshl_add_u64 v[114:115], v[28:29], 0, s[20:21]
	global_load_dword v88, v[114:115], off nt
	v_lshl_add_u64 v[116:117], v[26:27], 0, s[20:21]
	global_load_dword v89, v[116:117], off nt
	v_lshl_add_u64 v[110:111], v[24:25], 0, s[20:21]
	global_load_dword v90, v[110:111], off nt
	v_lshl_add_u64 v[112:113], v[22:23], 0, s[20:21]
	global_load_dword v91, v[112:113], off nt
	v_lshl_add_u64 v[114:115], v[20:21], 0, s[20:21]
	global_load_dword v92, v[114:115], off nt
	v_lshl_add_u64 v[116:117], v[18:19], 0, s[20:21]
	global_load_dword v93, v[116:117], off nt
	s_add_u32 s20, s20, 0x10000
	s_addc_u32 s21, s21, 0
	v_lshl_add_u64 v[110:111], v[32:33], 0, s[20:21]
	global_load_dword v94, v[110:111], off nt
	v_lshl_add_u64 v[112:113], v[30:31], 0, s[20:21]
	global_load_dword v95, v[112:113], off nt
	v_lshl_add_u64 v[114:115], v[28:29], 0, s[20:21]
	global_load_dword v96, v[114:115], off nt
	v_lshl_add_u64 v[116:117], v[26:27], 0, s[20:21]
	global_load_dword v97, v[116:117], off nt
	v_lshl_add_u64 v[110:111], v[24:25], 0, s[20:21]
	global_load_dword v98, v[110:111], off nt
	v_lshl_add_u64 v[112:113], v[22:23], 0, s[20:21]
	global_load_dword v99, v[112:113], off nt
	v_lshl_add_u64 v[114:115], v[20:21], 0, s[20:21]
	global_load_dword v100, v[114:115], off nt
	v_lshl_add_u64 v[116:117], v[18:19], 0, s[20:21]
	global_load_dword v101, v[116:117], off nt
	s_add_u32 s20, s20, 0x10000
	s_addc_u32 s21, s21, 0
	v_lshl_add_u64 v[110:111], v[32:33], 0, s[20:21]
	global_load_dword v102, v[110:111], off nt
	v_lshl_add_u64 v[112:113], v[30:31], 0, s[20:21]
	global_load_dword v103, v[112:113], off nt
	v_lshl_add_u64 v[114:115], v[28:29], 0, s[20:21]
	global_load_dword v104, v[114:115], off nt
	v_lshl_add_u64 v[116:117], v[26:27], 0, s[20:21]
	global_load_dword v105, v[116:117], off nt
	v_lshl_add_u64 v[110:111], v[24:25], 0, s[20:21]
	global_load_dword v106, v[110:111], off nt
	v_lshl_add_u64 v[112:113], v[22:23], 0, s[20:21]
	global_load_dword v107, v[112:113], off nt
	v_lshl_add_u64 v[114:115], v[20:21], 0, s[20:21]
	global_load_dword v108, v[114:115], off nt
	v_lshl_add_u64 v[116:117], v[18:19], 0, s[20:21]
	global_load_dword v109, v[116:117], off nt
	s_add_u32 s20, s20, 0x10000
	s_addc_u32 s21, s21, 0
	s_waitcnt vmcnt(30)
	ds_write2_b32 v35, v78, v79 offset1:66
	s_waitcnt vmcnt(28)
	ds_write2_b32 v35, v80, v81 offset0:132 offset1:198
	v_add_u32_e32 v118, 0x400, v35
	s_waitcnt vmcnt(26)
	ds_write2_b32 v118, v82, v83 offset0:8 offset1:74
	s_waitcnt vmcnt(24)
	ds_write2_b32 v118, v84, v85 offset0:140 offset1:206
	v_add_u32_e32 v35, 0x840, v35
	s_waitcnt vmcnt(22)
	ds_write2_b32 v35, v86, v87 offset1:66
	s_waitcnt vmcnt(20)
	ds_write2_b32 v35, v88, v89 offset0:132 offset1:198
	v_add_u32_e32 v118, 0x400, v35
	s_waitcnt vmcnt(18)
	ds_write2_b32 v118, v90, v91 offset0:8 offset1:74
	s_waitcnt vmcnt(16)
	ds_write2_b32 v118, v92, v93 offset0:140 offset1:206
	v_add_u32_e32 v35, 0x840, v35
	s_waitcnt vmcnt(14)
	ds_write2_b32 v35, v94, v95 offset1:66
	s_waitcnt vmcnt(12)
	ds_write2_b32 v35, v96, v97 offset0:132 offset1:198
	v_add_u32_e32 v118, 0x400, v35
	s_waitcnt vmcnt(10)
	ds_write2_b32 v118, v98, v99 offset0:8 offset1:74
	s_waitcnt vmcnt(8)
	ds_write2_b32 v118, v100, v101 offset0:140 offset1:206
	v_add_u32_e32 v35, 0x840, v35
	s_waitcnt vmcnt(6)
	ds_write2_b32 v35, v102, v103 offset1:66
	s_waitcnt vmcnt(4)
	ds_write2_b32 v35, v104, v105 offset0:132 offset1:198
	v_add_u32_e32 v118, 0x400, v35
	s_waitcnt vmcnt(2)
	ds_write2_b32 v118, v106, v107 offset0:8 offset1:74
	s_waitcnt vmcnt(0)
	ds_write2_b32 v118, v108, v109 offset0:140 offset1:206
	v_add_u32_e32 v35, 0x840, v35
	s_waitcnt lgkmcnt(0)
	v_readlane_b32 s14, v252, 12
	v_lshlrev_b32_e32 v22, 5, v34
	v_lshlrev_b64 v[16:17], 21, v[16:17]
	v_readlane_b32 s15, v252, 13
	ds_read2_b32 v[78:79], v40 offset1:33
	ds_read2_b32 v[80:81], v40 offset0:66 offset1:99
	ds_read2_b32 v[82:83], v40 offset0:132 offset1:165
	ds_read2_b32 v[84:85], v40 offset0:198 offset1:231
	ds_read2_b32 v[86:87], v40 offset0:8 offset1:41
	ds_read2_b32 v[88:89], v40 offset0:74 offset1:107
	ds_read2_b32 v[90:91], v40 offset0:140 offset1:173
	ds_read2_b32 v[92:93], v40 offset0:206 offset1:239
	ds_read2_b32 v[94:95], v40 offset0:16 offset1:49
	ds_read2_b32 v[96:97], v40 offset0:82 offset1:115
	ds_read2_b32 v[98:99], v40 offset0:148 offset1:181
	ds_read2_b32 v[100:101], v40 offset0:214 offset1:247
	ds_read2_b32 v[102:103], v40 offset0:24 offset1:57
	ds_read2_b32 v[104:105], v40 offset0:90 offset1:123
	ds_read2_b32 v[106:107], v40 offset0:156 offset1:189
	ds_read2_b32 v[108:109], v40 offset0:222 offset1:255
	s_waitcnt lgkmcnt(0)
	v_cvt_pk_bf16_f32 v120, v78, v79
	v_cvt_pk_bf16_f32 v121, v80, v81
	v_cvt_pk_bf16_f32 v122, v82, v83
	v_cvt_pk_bf16_f32 v123, v84, v85
	v_cvt_pk_bf16_f32 v124, v86, v87
	v_cvt_pk_bf16_f32 v125, v88, v89
	v_cvt_pk_bf16_f32 v126, v90, v91
	v_cvt_pk_bf16_f32 v127, v92, v93
	v_cvt_pk_bf16_f32 v128, v94, v95
	v_cvt_pk_bf16_f32 v129, v96, v97
	v_cvt_pk_bf16_f32 v130, v98, v99
	v_cvt_pk_bf16_f32 v131, v100, v101
	v_cvt_pk_bf16_f32 v132, v102, v103
	v_cvt_pk_bf16_f32 v133, v104, v105
	v_cvt_pk_bf16_f32 v134, v106, v107
	v_cvt_pk_bf16_f32 v135, v108, v109
	v_add_u32_e32 v0, 0xffffb400, v0
	v_and_b32_e32 v26, 0x3e0, v22
	v_lshl_add_u64 v[16:17], s[14:15], 0, v[16:17]
	v_lshl_add_u64 v[16:17], v[0:1], 1, v[16:17]
	v_lshlrev_b32_e32 v0, 1, v2
	v_or_b32_e32 v27, v26, v39
	v_lshl_add_u64 v[24:25], v[16:17], 0, v[0:1]
	v_lshlrev_b32_e32 v0, 11, v27
	v_lshl_add_u64 v[16:17], v[24:25], 0, v[0:1]
	global_store_dwordx4 v[16:17], v[120:123], off nt
	v_or_b32_e32 v0, v26, v41
	v_lshlrev_b32_e32 v0, 11, v0
	v_lshl_add_u64 v[22:23], v[24:25], 0, v[0:1]
	global_store_dwordx4 v[22:23], v[124:127], off nt
	v_or_b32_e32 v0, v26, v42
	v_lshlrev_b32_e32 v0, 11, v0
	v_lshl_add_u64 v[22:23], v[24:25], 0, v[0:1]
	global_store_dwordx4 v[22:23], v[128:131], off nt
	v_or_b32_e32 v0, v26, v43
	v_lshlrev_b32_e32 v0, 11, v0
	v_lshl_add_u64 v[20:21], v[24:25], 0, v[0:1]
	global_store_dwordx4 v[20:21], v[132:135], off nt
	s_waitcnt lgkmcnt(0)

; #define LAS __attribute__((address_space(3)))
; __device__ __forceinline__ unsigned cvt_pk_bf16(float lo, float hi) { unsigned r; asm volatile("v_cvt_pk_bf16_f32 %0, %1, %2" : "=v"(r) : "v"(lo), "v"(hi)); return r; }
; #define LDS_WAIT() asm volatile("s_waitcnt lgkmcnt(0)" ::: "memory")
; #pragma unroll 8
;     for (int i = 0; i < 32; ++i) { const int kk = 2 * i + (lane >> 5); scr[kk * 33 + (lane & 31)] = __builtin_nontemporal_load(W + (size_t)(k0 + kk) * N + n0 + (lane & 31)); }
;     LDS_WAIT(); asm volatile("" ::: "memory");
;     const int c = lane & 7;
; #pragma unroll
;     for (int j = 0; j < 4; ++j) { const int n = (lane >> 3) + 8 * j; const LAS float* s = scr + (8 * c) * 33 + n;
;         u32x4 o; o.x = cvt_pk_bf16(s[0 * 33] * wscale, s[1 * 33] * wscale); o.y = cvt_pk_bf16(s[2 * 33] * wscale, s[3 * 33] * wscale); o.z = cvt_pk_bf16(s[4 * 33] * wscale, s[5 * 33] * wscale); o.w = cvt_pk_bf16(s[6 * 33] * wscale, s[7 * 33] * wscale);
;         __builtin_nontemporal_store(o, (u32x4*)(WT + (size_t)(drow0 + n0 + n) * K + k0 + 8 * c)); }
;     LDS_WAIT(); asm volatile("" ::: "memory");
; __device__ __forceinline__ void prologue_a(const Args& a, LAS unsigned char* lds, int tid, int G) {
;     ...
;                 transpose_item(a.in[I_WIN] + (size_t)l * DM * INC, INC, kb * 64, nb * 32, (bf16_t*)(ws + WS_WIN) + (size_t)l * INC * DM, DM, 0, scr, lane);
.LBB0_38:
	v_lshl_add_u64 v[110:111], v[32:33], 0, s[20:21]
	global_load_dword v78, v[110:111], off nt
	v_lshl_add_u64 v[112:113], v[30:31], 0, s[20:21]
	global_load_dword v79, v[112:113], off nt
	v_lshl_add_u64 v[114:115], v[28:29], 0, s[20:21]
	global_load_dword v80, v[114:115], off nt
	v_lshl_add_u64 v[116:117], v[26:27], 0, s[20:21]
	global_load_dword v81, v[116:117], off nt
	v_lshl_add_u64 v[110:111], v[24:25], 0, s[20:21]
	global_load_dword v82, v[110:111], off nt
	v_lshl_add_u64 v[112:113], v[22:23], 0, s[20:21]
	global_load_dword v83, v[112:113], off nt
	v_lshl_add_u64 v[114:115], v[20:21], 0, s[20:21]
	global_load_dword v84, v[114:115], off nt
	v_lshl_add_u64 v[116:117], v[18:19], 0, s[20:21]
	global_load_dword v85, v[116:117], off nt
	s_add_u32 s20, s20, 0x28000
	s_addc_u32 s21, s21, 0
	v_lshl_add_u64 v[110:111], v[32:33], 0, s[20:21]
	global_load_dword v86, v[110:111], off nt
	v_lshl_add_u64 v[112:113], v[30:31], 0, s[20:21]
	global_load_dword v87, v[112:113], off nt
	v_lshl_add_u64 v[114:115], v[28:29], 0, s[20:21]
	global_load_dword v88, v[114:115], off nt
	v_lshl_add_u64 v[116:117], v[26:27], 0, s[20:21]
	global_load_dword v89, v[116:117], off nt
	v_lshl_add_u64 v[110:111], v[24:25], 0, s[20:21]
	global_load_dword v90, v[110:111], off nt
	v_lshl_add_u64 v[112:113], v[22:23], 0, s[20:21]
	global_load_dword v91, v[112:113], off nt
	v_lshl_add_u64 v[114:115], v[20:21], 0, s[20:21]
	global_load_dword v92, v[114:115], off nt
	v_lshl_add_u64 v[116:117], v[18:19], 0, s[20:21]
	global_load_dword v93, v[116:117], off nt
	s_add_u32 s20, s20, 0x28000
	s_addc_u32 s21, s21, 0
	v_lshl_add_u64 v[110:111], v[32:33], 0, s[20:21]
	global_load_dword v94, v[110:111], off nt
	v_lshl_add_u64 v[112:113], v[30:31], 0, s[20:21]
	global_load_dword v95, v[112:113], off nt
	v_lshl_add_u64 v[114:115], v[28:29], 0, s[20:21]
	global_load_dword v96, v[114:115], off nt
	v_lshl_add_u64 v[116:117], v[26:27], 0, s[20:21]
	global_load_dword v97, v[116:117], off nt
	v_lshl_add_u64 v[110:111], v[24:25], 0, s[20:21]
	global_load_dword v98, v[110:111], off nt
	v_lshl_add_u64 v[112:113], v[22:23], 0, s[20:21]
	global_load_dword v99, v[112:113], off nt
	v_lshl_add_u64 v[114:115], v[20:21], 0, s[20:21]
	global_load_dword v100, v[114:115], off nt
	v_lshl_add_u64 v[116:117], v[18:19], 0, s[20:21]
	global_load_dword v101, v[116:117], off nt
	s_add_u32 s20, s20, 0x28000
	s_addc_u32 s21, s21, 0
	v_lshl_add_u64 v[110:111], v[32:33], 0, s[20:21]
	global_load_dword v102, v[110:111], off nt
	v_lshl_add_u64 v[112:113], v[30:31], 0, s[20:21]
	global_load_dword v103, v[112:113], off nt
	v_lshl_add_u64 v[114:115], v[28:29], 0, s[20:21]
	global_load_dword v104, v[114:115], off nt
	v_lshl_add_u64 v[116:117], v[26:27], 0, s[20:21]
	global_load_dword v105, v[116:117], off nt
	v_lshl_add_u64 v[110:111], v[24:25], 0, s[20:21]
	global_load_dword v106, v[110:111], off nt
	v_lshl_add_u64 v[112:113], v[22:23], 0, s[20:21]
	global_load_dword v107, v[112:113], off nt
	v_lshl_add_u64 v[114:115], v[20:21], 0, s[20:21]
	global_load_dword v108, v[114:115], off nt
	v_lshl_add_u64 v[116:117], v[18:19], 0, s[20:21]
	global_load_dword v109, v[116:117], off nt
	s_add_u32 s20, s20, 0x28000
	s_addc_u32 s21, s21, 0
	s_waitcnt vmcnt(30)
	ds_write2_b32 v0, v78, v79 offset1:66
	s_waitcnt vmcnt(28)
	ds_write2_b32 v0, v80, v81 offset0:132 offset1:198
	v_add_u32_e32 v118, 0x400, v0
	s_waitcnt vmcnt(26)
	ds_write2_b32 v118, v82, v83 offset0:8 offset1:74
	s_waitcnt vmcnt(24)
	ds_write2_b32 v118, v84, v85 offset0:140 offset1:206
	v_add_u32_e32 v0, 0x840, v0
	s_waitcnt vmcnt(22)
	ds_write2_b32 v0, v86, v87 offset1:66
	s_waitcnt vmcnt(20)
	ds_write2_b32 v0, v88, v89 offset0:132 offset1:198
	v_add_u32_e32 v118, 0x400, v0
	s_waitcnt vmcnt(18)
	ds_write2_b32 v118, v90, v91 offset0:8 offset1:74
	s_waitcnt vmcnt(16)
	ds_write2_b32 v118, v92, v93 offset0:140 offset1:206
	v_add_u32_e32 v0, 0x840, v0
	s_waitcnt vmcnt(14)
	ds_write2_b32 v0, v94, v95 offset1:66
	s_waitcnt vmcnt(12)
	ds_write2_b32 v0, v96, v97 offset0:132 offset1:198
	v_add_u32_e32 v118, 0x400, v0
	s_waitcnt vmcnt(10)
	ds_write2_b32 v118, v98, v99 offset0:8 offset1:74
	s_waitcnt vmcnt(8)
	ds_write2_b32 v118, v100, v101 offset0:140 offset1:206
	v_add_u32_e32 v0, 0x840, v0
	s_waitcnt vmcnt(6)
	ds_write2_b32 v0, v102, v103 offset1:66
	s_waitcnt vmcnt(4)
	ds_write2_b32 v0, v104, v105 offset0:132 offset1:198
	v_add_u32_e32 v118, 0x400, v0
	s_waitcnt vmcnt(2)
	ds_write2_b32 v118, v106, v107 offset0:8 offset1:74
	s_waitcnt vmcnt(0)
	ds_write2_b32 v118, v108, v109 offset0:140 offset1:206
	v_add_u32_e32 v0, 0x840, v0
	s_waitcnt lgkmcnt(0)
	v_readlane_b32 s14, v252, 14
	v_mul_hi_i32_i24_e32 v23, 0x500000, v16
	v_mul_i32_i24_e32 v22, 0x500000, v16
	v_readlane_b32 s15, v252, 15
	ds_read2_b32 v[78:79], v40 offset1:33
	ds_read2_b32 v[80:81], v40 offset0:66 offset1:99
	ds_read2_b32 v[82:83], v40 offset0:132 offset1:165
	ds_read2_b32 v[84:85], v40 offset0:198 offset1:231
	ds_read2_b32 v[86:87], v40 offset0:8 offset1:41
	ds_read2_b32 v[88:89], v40 offset0:74 offset1:107
	ds_read2_b32 v[90:91], v40 offset0:140 offset1:173
	ds_read2_b32 v[92:93], v40 offset0:206 offset1:239
	ds_read2_b32 v[94:95], v40 offset0:16 offset1:49
	ds_read2_b32 v[96:97], v40 offset0:82 offset1:115
	ds_read2_b32 v[98:99], v40 offset0:148 offset1:181
	ds_read2_b32 v[100:101], v40 offset0:214 offset1:247
	ds_read2_b32 v[102:103], v40 offset0:24 offset1:57
	ds_read2_b32 v[104:105], v40 offset0:90 offset1:123
	ds_read2_b32 v[106:107], v40 offset0:156 offset1:189
	ds_read2_b32 v[108:109], v40 offset0:222 offset1:255
	s_waitcnt lgkmcnt(0)
	v_cvt_pk_bf16_f32 v120, v78, v79
	v_cvt_pk_bf16_f32 v121, v80, v81
	v_cvt_pk_bf16_f32 v122, v82, v83
	v_cvt_pk_bf16_f32 v123, v84, v85
	v_cvt_pk_bf16_f32 v124, v86, v87
	v_cvt_pk_bf16_f32 v125, v88, v89
	v_cvt_pk_bf16_f32 v126, v90, v91
	v_cvt_pk_bf16_f32 v127, v92, v93
	v_cvt_pk_bf16_f32 v128, v94, v95
	v_cvt_pk_bf16_f32 v129, v96, v97
	v_cvt_pk_bf16_f32 v130, v98, v99
	v_cvt_pk_bf16_f32 v131, v100, v101
	v_cvt_pk_bf16_f32 v132, v102, v103
	v_cvt_pk_bf16_f32 v133, v104, v105
	v_cvt_pk_bf16_f32 v134, v106, v107
	v_cvt_pk_bf16_f32 v135, v108, v109
	v_lshlrev_b32_sdwa v0, v188, v34 dst_sel:DWORD dst_unused:UNUSED_PAD src0_sel:DWORD src1_sel:WORD_0
	v_lshl_add_u64 v[22:23], s[14:15], 0, v[22:23]
	v_or_b32_e32 v16, v39, v17
	v_lshl_add_u64 v[22:23], v[22:23], 0, v[0:1]
	v_lshlrev_b32_e32 v0, 1, v2
	v_lshl_add_u64 v[22:23], v[22:23], 0, v[0:1]
	v_lshlrev_b32_e32 v0, 11, v16
	v_lshl_add_u64 v[26:27], v[22:23], 0, v[0:1]
	global_store_dwordx4 v[26:27], v[120:123], off nt
	v_or_b32_e32 v0, v41, v17
	v_lshlrev_b32_e32 v0, 11, v0
	v_lshl_add_u64 v[26:27], v[22:23], 0, v[0:1]
	global_store_dwordx4 v[26:27], v[124:127], off nt
	v_or_b32_e32 v0, v42, v17
	v_lshlrev_b32_e32 v0, 11, v0
	v_lshl_add_u64 v[26:27], v[22:23], 0, v[0:1]
	v_or_b32_e32 v0, v43, v17
	global_store_dwordx4 v[26:27], v[128:131], off nt
	v_lshlrev_b32_e32 v0, 11, v0
	v_lshl_add_u64 v[16:17], v[22:23], 0, v[0:1]
	global_store_dwordx4 v[16:17], v[132:135], off nt
	s_waitcnt lgkmcnt(0)

; #pragma unroll 8
;     for (int i = 0; i < 32; ++i) { const int kk = 2 * i + (lane >> 5); scr[kk * 33 + (lane & 31)] = __builtin_nontemporal_load(W + (size_t)(k0 + kk) * N + n0 + (lane & 31)); }
; __device__ __forceinline__ void prologue_a(const Args& a, LAS unsigned char* lds, int tid, int G) {
;     ...
;                 r -= 5632; const int sub = r / 1408, rr = r % 1408, kb = rr / 32, nb = rr % 32;
;                 const float* W = a.in[I_WD] + (size_t)(l * 2 + sub) * DFF * DM;
;                 bf16_t* WT = (bf16_t*)(ws + WS_WD) + (size_t)(l * 2 + sub) * DM * DFF;
;                 transpose_item(W, DM, kb * 64, nb * 32, WT, DFF, 0, scr, lane);
.LBB0_43:
	v_lshl_add_u64 v[110:111], v[24:25], 0, s[18:19]
	global_load_dword v78, v[110:111], off nt
	v_add_co_u32_e32 v112, vcc, 0x2000, v110
	s_nop 1
	v_addc_co_u32_e32 v113, vcc, 0, v111, vcc
	global_load_dword v79, v[112:113], off nt
	v_add_co_u32_e32 v114, vcc, 0x4000, v110
	s_nop 1
	v_addc_co_u32_e32 v115, vcc, 0, v111, vcc
	global_load_dword v80, v[114:115], off nt
	v_add_co_u32_e32 v116, vcc, 0x6000, v110
	s_nop 1
	v_addc_co_u32_e32 v117, vcc, 0, v111, vcc
	global_load_dword v81, v[116:117], off nt
	v_lshl_add_u64 v[110:111], v[22:23], 0, s[18:19]
	global_load_dword v82, v[110:111], off nt
	v_lshl_add_u64 v[112:113], v[20:21], 0, s[18:19]
	global_load_dword v83, v[112:113], off nt
	v_lshl_add_u64 v[114:115], v[18:19], 0, s[18:19]
	global_load_dword v84, v[114:115], off nt
	v_lshl_add_u64 v[116:117], v[16:17], 0, s[18:19]
	global_load_dword v85, v[116:117], off nt
	s_add_u32 s18, s18, 0x10000
	s_addc_u32 s19, s19, 0
	v_lshl_add_u64 v[110:111], v[24:25], 0, s[18:19]
	global_load_dword v86, v[110:111], off nt
	v_add_co_u32_e32 v112, vcc, 0x2000, v110
	s_nop 1
	v_addc_co_u32_e32 v113, vcc, 0, v111, vcc
	global_load_dword v87, v[112:113], off nt
	v_add_co_u32_e32 v114, vcc, 0x4000, v110
	s_nop 1
	v_addc_co_u32_e32 v115, vcc, 0, v111, vcc
	global_load_dword v88, v[114:115], off nt
	v_add_co_u32_e32 v116, vcc, 0x6000, v110
	s_nop 1
	v_addc_co_u32_e32 v117, vcc, 0, v111, vcc
	global_load_dword v89, v[116:117], off nt
	v_lshl_add_u64 v[110:111], v[22:23], 0, s[18:19]
	global_load_dword v90, v[110:111], off nt
	v_lshl_add_u64 v[112:113], v[20:21], 0, s[18:19]
	global_load_dword v91, v[112:113], off nt
	v_lshl_add_u64 v[114:115], v[18:19], 0, s[18:19]
	global_load_dword v92, v[114:115], off nt
	v_lshl_add_u64 v[116:117], v[16:17], 0, s[18:19]
	global_load_dword v93, v[116:117], off nt
	s_add_u32 s18, s18, 0x10000
	s_addc_u32 s19, s19, 0
	v_lshl_add_u64 v[110:111], v[24:25], 0, s[18:19]
	global_load_dword v94, v[110:111], off nt
	v_add_co_u32_e32 v112, vcc, 0x2000, v110
	s_nop 1
	v_addc_co_u32_e32 v113, vcc, 0, v111, vcc
	global_load_dword v95, v[112:113], off nt
	v_add_co_u32_e32 v114, vcc, 0x4000, v110
	s_nop 1
	v_addc_co_u32_e32 v115, vcc, 0, v111, vcc
	global_load_dword v96, v[114:115], off nt
	v_add_co_u32_e32 v116, vcc, 0x6000, v110
	s_nop 1
	v_addc_co_u32_e32 v117, vcc, 0, v111, vcc
	global_load_dword v97, v[116:117], off nt
	v_lshl_add_u64 v[110:111], v[22:23], 0, s[18:19]
	global_load_dword v98, v[110:111], off nt
	v_lshl_add_u64 v[112:113], v[20:21], 0, s[18:19]
	global_load_dword v99, v[112:113], off nt
	v_lshl_add_u64 v[114:115], v[18:19], 0, s[18:19]
	global_load_dword v100, v[114:115], off nt
	v_lshl_add_u64 v[116:117], v[16:17], 0, s[18:19]
	global_load_dword v101, v[116:117], off nt
	s_add_u32 s18, s18, 0x10000
	s_addc_u32 s19, s19, 0
	v_lshl_add_u64 v[110:111], v[24:25], 0, s[18:19]
	global_load_dword v102, v[110:111], off nt
	v_add_co_u32_e32 v112, vcc, 0x2000, v110
	s_nop 1
	v_addc_co_u32_e32 v113, vcc, 0, v111, vcc
	global_load_dword v103, v[112:113], off nt
	v_add_co_u32_e32 v114, vcc, 0x4000, v110
	s_nop 1
	v_addc_co_u32_e32 v115, vcc, 0, v111, vcc
	global_load_dword v104, v[114:115], off nt
	v_add_co_u32_e32 v116, vcc, 0x6000, v110
	s_nop 1
	v_addc_co_u32_e32 v117, vcc, 0, v111, vcc
	global_load_dword v105, v[116:117], off nt
	v_lshl_add_u64 v[110:111], v[22:23], 0, s[18:19]
	global_load_dword v106, v[110:111], off nt
	v_lshl_add_u64 v[112:113], v[20:21], 0, s[18:19]
	global_load_dword v107, v[112:113], off nt
	v_lshl_add_u64 v[114:115], v[18:19], 0, s[18:19]
	global_load_dword v108, v[114:115], off nt
	v_lshl_add_u64 v[116:117], v[16:17], 0, s[18:19]
	global_load_dword v109, v[116:117], off nt
	s_add_u32 s18, s18, 0x10000
	s_addc_u32 s19, s19, 0
	s_waitcnt vmcnt(30)
	ds_write2_b32 v0, v78, v79 offset1:66
	s_waitcnt vmcnt(28)
; #define LAS __attribute__((address_space(3)))
; __device__ __forceinline__ unsigned cvt_pk_bf16(float lo, float hi) { unsigned r; asm volatile("v_cvt_pk_bf16_f32 %0, %1, %2" : "=v"(r) : "v"(lo), "v"(hi)); return r; }
; #define LDS_WAIT() asm volatile("s_waitcnt lgkmcnt(0)" ::: "memory")
;     ...
;     for (int i = 0; i < 32; ++i) { const int kk = 2 * i + (lane >> 5); scr[kk * 33 + (lane & 31)] = __builtin_nontemporal_load(W + (size_t)(k0 + kk) * N + n0 + (lane & 31)); }
;     LDS_WAIT(); asm volatile("" ::: "memory");
;     const int c = lane & 7;
; #pragma unroll
;     for (int j = 0; j < 4; ++j) { const int n = (lane >> 3) + 8 * j; const LAS float* s = scr + (8 * c) * 33 + n;
;         u32x4 o; o.x = cvt_pk_bf16(s[0 * 33] * wscale, s[1 * 33] * wscale); o.y = cvt_pk_bf16(s[2 * 33] * wscale, s[3 * 33] * wscale); o.z = cvt_pk_bf16(s[4 * 33] * wscale, s[5 * 33] * wscale); o.w = cvt_pk_bf16(s[6 * 33] * wscale, s[7 * 33] * wscale);
;         __builtin_nontemporal_store(o, (u32x4*)(WT + (size_t)(drow0 + n0 + n) * K + k0 + 8 * c)); }
;     LDS_WAIT(); asm volatile("" ::: "memory");
; __device__ __forceinline__ void prologue_a(const Args& a, LAS unsigned char* lds, int tid, int G) {
;     ...
;                 r -= 5632; const int sub = r / 1408, rr = r % 1408, kb = rr / 32, nb = rr % 32;
;                 const float* W = a.in[I_WD] + (size_t)(l * 2 + sub) * DFF * DM;
;                 bf16_t* WT = (bf16_t*)(ws + WS_WD) + (size_t)(l * 2 + sub) * DM * DFF;
;                 transpose_item(W, DM, kb * 64, nb * 32, WT, DFF, 0, scr, lane);
	ds_write2_b32 v0, v80, v81 offset0:132 offset1:198
	v_add_u32_e32 v118, 0x400, v0
	s_waitcnt vmcnt(26)
	ds_write2_b32 v118, v82, v83 offset0:8 offset1:74
	s_waitcnt vmcnt(24)
	ds_write2_b32 v118, v84, v85 offset0:140 offset1:206
	v_add_u32_e32 v0, 0x840, v0
	s_waitcnt vmcnt(22)
	ds_write2_b32 v0, v86, v87 offset1:66
	s_waitcnt vmcnt(20)
	ds_write2_b32 v0, v88, v89 offset0:132 offset1:198
	v_add_u32_e32 v118, 0x400, v0
	s_waitcnt vmcnt(18)
	ds_write2_b32 v118, v90, v91 offset0:8 offset1:74
	s_waitcnt vmcnt(16)
	ds_write2_b32 v118, v92, v93 offset0:140 offset1:206
	v_add_u32_e32 v0, 0x840, v0
	s_waitcnt vmcnt(14)
	ds_write2_b32 v0, v94, v95 offset1:66
	s_waitcnt vmcnt(12)
	ds_write2_b32 v0, v96, v97 offset0:132 offset1:198
	v_add_u32_e32 v118, 0x400, v0
	s_waitcnt vmcnt(10)
	ds_write2_b32 v118, v98, v99 offset0:8 offset1:74
	s_waitcnt vmcnt(8)
	ds_write2_b32 v118, v100, v101 offset0:140 offset1:206
	v_add_u32_e32 v0, 0x840, v0
	s_waitcnt vmcnt(6)
	ds_write2_b32 v0, v102, v103 offset1:66
	s_waitcnt vmcnt(4)
	ds_write2_b32 v0, v104, v105 offset0:132 offset1:198
	v_add_u32_e32 v118, 0x400, v0
	s_waitcnt vmcnt(2)
	ds_write2_b32 v118, v106, v107 offset0:8 offset1:74
	s_waitcnt vmcnt(0)
	ds_write2_b32 v118, v108, v109 offset0:140 offset1:206
	v_add_u32_e32 v0, 0x840, v0
	v_lshlrev_b32_e32 v22, 5, v28
	v_mul_hi_i32_i24_e32 v21, 0x580000, v26
	v_mul_i32_i24_e32 v20, 0x580000, v26
	s_waitcnt lgkmcnt(0)
	v_lshlrev_b32_e32 v0, 1, v27
	v_and_b32_e32 v26, 0x3e0, v22
	v_lshl_add_u64 v[20:21], s[22:23], 0, v[20:21]
	v_lshl_add_u64 v[20:21], v[20:21], 0, v[0:1]
	v_lshlrev_b32_e32 v0, 1, v2
	v_or_b32_e32 v24, v26, v39
	ds_read2_b32 v[78:79], v40 offset1:33
	ds_read2_b32 v[80:81], v40 offset0:66 offset1:99
	ds_read2_b32 v[82:83], v40 offset0:132 offset1:165
	ds_read2_b32 v[84:85], v40 offset0:198 offset1:231
	ds_read2_b32 v[86:87], v40 offset0:8 offset1:41
	ds_read2_b32 v[88:89], v40 offset0:74 offset1:107
	ds_read2_b32 v[90:91], v40 offset0:140 offset1:173
	ds_read2_b32 v[92:93], v40 offset0:206 offset1:239
	ds_read2_b32 v[94:95], v40 offset0:16 offset1:49
	ds_read2_b32 v[96:97], v40 offset0:82 offset1:115
	ds_read2_b32 v[98:99], v40 offset0:148 offset1:181
	ds_read2_b32 v[100:101], v40 offset0:214 offset1:247
	ds_read2_b32 v[102:103], v40 offset0:24 offset1:57
	ds_read2_b32 v[104:105], v40 offset0:90 offset1:123
	ds_read2_b32 v[106:107], v40 offset0:156 offset1:189
	ds_read2_b32 v[108:109], v40 offset0:222 offset1:255
	s_waitcnt lgkmcnt(0)
	v_cvt_pk_bf16_f32 v120, v78, v79
	v_cvt_pk_bf16_f32 v121, v80, v81
	v_cvt_pk_bf16_f32 v122, v82, v83
	v_cvt_pk_bf16_f32 v123, v84, v85
	v_cvt_pk_bf16_f32 v124, v86, v87
	v_cvt_pk_bf16_f32 v125, v88, v89
	v_cvt_pk_bf16_f32 v126, v90, v91
	v_cvt_pk_bf16_f32 v127, v92, v93
	v_cvt_pk_bf16_f32 v128, v94, v95
	v_cvt_pk_bf16_f32 v129, v96, v97
	v_cvt_pk_bf16_f32 v130, v98, v99
	v_cvt_pk_bf16_f32 v131, v100, v101
	v_cvt_pk_bf16_f32 v132, v102, v103
	v_cvt_pk_bf16_f32 v133, v104, v105
	v_cvt_pk_bf16_f32 v134, v106, v107
	v_cvt_pk_bf16_f32 v135, v108, v109
	v_lshl_add_u64 v[20:21], v[20:21], 0, v[0:1]
	v_mul_u32_u24_e32 v0, 0xb00, v24
	v_lshlrev_b32_e32 v0, 1, v0
	v_lshl_add_u64 v[24:25], v[20:21], 0, v[0:1]
	v_or_b32_e32 v0, v26, v41
	v_mul_u32_u24_e32 v0, 0xb00, v0
	global_store_dwordx4 v[24:25], v[120:123], off nt
	v_lshlrev_b32_e32 v0, 1, v0
	v_lshl_add_u64 v[24:25], v[20:21], 0, v[0:1]
	v_or_b32_e32 v0, v26, v42
	v_mul_u32_u24_e32 v0, 0xb00, v0
	global_store_dwordx4 v[24:25], v[124:127], off nt
	v_lshlrev_b32_e32 v0, 1, v0
	v_lshl_add_u64 v[24:25], v[20:21], 0, v[0:1]
	v_or_b32_e32 v0, v26, v43
	v_mul_u32_u24_e32 v0, 0xb00, v0
	global_store_dwordx4 v[24:25], v[128:131], off nt
	v_lshlrev_b32_e32 v0, 1, v0
	v_lshl_add_u64 v[20:21], v[20:21], 0, v[0:1]
	global_store_dwordx4 v[20:21], v[132:135], off nt
	s_waitcnt lgkmcnt(0)

; #pragma unroll 8
;     for (int i = 0; i < 32; ++i) { const int kk = 2 * i + (lane >> 5); scr[kk * 33 + (lane & 31)] = __builtin_nontemporal_load(W + (size_t)(k0 + kk) * N + n0 + (lane & 31)); }
; __device__ __forceinline__ void prologue_a(const Args& a, LAS unsigned char* lds, int tid, int G) {
;     ...
;                 const int up = r >= 2816; if (up) r -= 2816;
;                 const int sub = r / 1408, rr = r % 1408, kb = rr / 88, nb = rr % 88, n0 = nb * 32;
;                 const float* W = a.in[up ? I_WU : I_WG] + (size_t)(l * 2 + sub) * DM * DFF;
;                 bf16_t* WT = (bf16_t*)(ws + WS_WGU) + (size_t)(l * 2 + sub) * NGU * DM;
;                 transpose_item(W, DFF, kb * 64, n0, WT, DM, 256 * (n0 >> 7) + (up ? 128 : 0) + (n0 & 127) - n0, scr, lane, up ? (1.0f / LOG2E) : LOG2E);
.LBB0_50:
	v_lshl_add_u64 v[110:111], v[36:37], 0, s[12:13]
	global_load_dword v78, v[110:111], off nt
	v_lshl_add_u64 v[112:113], v[34:35], 0, s[12:13]
	global_load_dword v79, v[112:113], off nt
	v_lshl_add_u64 v[114:115], v[32:33], 0, s[12:13]
	global_load_dword v80, v[114:115], off nt
	v_lshl_add_u64 v[116:117], v[30:31], 0, s[12:13]
	global_load_dword v81, v[116:117], off nt
	v_lshl_add_u64 v[110:111], v[28:29], 0, s[12:13]
	global_load_dword v82, v[110:111], off nt
	v_lshl_add_u64 v[112:113], v[26:27], 0, s[12:13]
	global_load_dword v83, v[112:113], off nt
	v_lshl_add_u64 v[114:115], v[24:25], 0, s[12:13]
	global_load_dword v84, v[114:115], off nt
	v_lshl_add_u64 v[116:117], v[22:23], 0, s[12:13]
	global_load_dword v85, v[116:117], off nt
	s_add_u32 s12, s12, 0x2c000
	s_addc_u32 s13, s13, 0
	v_lshl_add_u64 v[110:111], v[36:37], 0, s[12:13]
	global_load_dword v86, v[110:111], off nt
	v_lshl_add_u64 v[112:113], v[34:35], 0, s[12:13]
	global_load_dword v87, v[112:113], off nt
	v_lshl_add_u64 v[114:115], v[32:33], 0, s[12:13]
	global_load_dword v88, v[114:115], off nt
	v_lshl_add_u64 v[116:117], v[30:31], 0, s[12:13]
	global_load_dword v89, v[116:117], off nt
	v_lshl_add_u64 v[110:111], v[28:29], 0, s[12:13]
	global_load_dword v90, v[110:111], off nt
	v_lshl_add_u64 v[112:113], v[26:27], 0, s[12:13]
	global_load_dword v91, v[112:113], off nt
	v_lshl_add_u64 v[114:115], v[24:25], 0, s[12:13]
	global_load_dword v92, v[114:115], off nt
	v_lshl_add_u64 v[116:117], v[22:23], 0, s[12:13]
	global_load_dword v93, v[116:117], off nt
	s_add_u32 s12, s12, 0x2c000
	s_addc_u32 s13, s13, 0
	v_lshl_add_u64 v[110:111], v[36:37], 0, s[12:13]
	global_load_dword v94, v[110:111], off nt
	v_lshl_add_u64 v[112:113], v[34:35], 0, s[12:13]
	global_load_dword v95, v[112:113], off nt
	v_lshl_add_u64 v[114:115], v[32:33], 0, s[12:13]
	global_load_dword v96, v[114:115], off nt
	v_lshl_add_u64 v[116:117], v[30:31], 0, s[12:13]
	global_load_dword v97, v[116:117], off nt
	v_lshl_add_u64 v[110:111], v[28:29], 0, s[12:13]
	global_load_dword v98, v[110:111], off nt
	v_lshl_add_u64 v[112:113], v[26:27], 0, s[12:13]
	global_load_dword v99, v[112:113], off nt
	v_lshl_add_u64 v[114:115], v[24:25], 0, s[12:13]
	global_load_dword v100, v[114:115], off nt
	v_lshl_add_u64 v[116:117], v[22:23], 0, s[12:13]
	global_load_dword v101, v[116:117], off nt
	s_add_u32 s12, s12, 0x2c000
	s_addc_u32 s13, s13, 0
	v_lshl_add_u64 v[110:111], v[36:37], 0, s[12:13]
	global_load_dword v102, v[110:111], off nt
	v_lshl_add_u64 v[112:113], v[34:35], 0, s[12:13]
	global_load_dword v103, v[112:113], off nt
	v_lshl_add_u64 v[114:115], v[32:33], 0, s[12:13]
	global_load_dword v104, v[114:115], off nt
	v_lshl_add_u64 v[116:117], v[30:31], 0, s[12:13]
	global_load_dword v105, v[116:117], off nt
	v_lshl_add_u64 v[110:111], v[28:29], 0, s[12:13]
	global_load_dword v106, v[110:111], off nt
	v_lshl_add_u64 v[112:113], v[26:27], 0, s[12:13]
	global_load_dword v107, v[112:113], off nt
	v_lshl_add_u64 v[114:115], v[24:25], 0, s[12:13]
	global_load_dword v108, v[114:115], off nt
	v_lshl_add_u64 v[116:117], v[22:23], 0, s[12:13]
	global_load_dword v109, v[116:117], off nt
	s_add_u32 s12, s12, 0x2c000
	s_addc_u32 s13, s13, 0
	s_waitcnt vmcnt(30)
	ds_write2_b32 v19, v78, v79 offset1:66
	s_waitcnt vmcnt(28)
	ds_write2_b32 v19, v80, v81 offset0:132 offset1:198
	v_add_u32_e32 v118, 0x400, v19
	s_waitcnt vmcnt(26)
	ds_write2_b32 v118, v82, v83 offset0:8 offset1:74
	s_waitcnt vmcnt(24)
	ds_write2_b32 v118, v84, v85 offset0:140 offset1:206
	v_add_u32_e32 v19, 0x840, v19
	s_waitcnt vmcnt(22)
	ds_write2_b32 v19, v86, v87 offset1:66
	s_waitcnt vmcnt(20)
	ds_write2_b32 v19, v88, v89 offset0:132 offset1:198
	v_add_u32_e32 v118, 0x400, v19
	s_waitcnt vmcnt(18)
	ds_write2_b32 v118, v90, v91 offset0:8 offset1:74
	s_waitcnt vmcnt(16)
	ds_write2_b32 v118, v92, v93 offset0:140 offset1:206
	v_add_u32_e32 v19, 0x840, v19
	s_waitcnt vmcnt(14)
	ds_write2_b32 v19, v94, v95 offset1:66
	s_waitcnt vmcnt(12)
	ds_write2_b32 v19, v96, v97 offset0:132 offset1:198
	v_add_u32_e32 v118, 0x400, v19
	s_waitcnt vmcnt(10)
; #define LAS __attribute__((address_space(3)))
; __device__ __forceinline__ unsigned cvt_pk_bf16(float lo, float hi) { unsigned r; asm volatile("v_cvt_pk_bf16_f32 %0, %1, %2" : "=v"(r) : "v"(lo), "v"(hi)); return r; }
; #define LDS_WAIT() asm volatile("s_waitcnt lgkmcnt(0)" ::: "memory")
;     ...
;     for (int i = 0; i < 32; ++i) { const int kk = 2 * i + (lane >> 5); scr[kk * 33 + (lane & 31)] = __builtin_nontemporal_load(W + (size_t)(k0 + kk) * N + n0 + (lane & 31)); }
;     LDS_WAIT(); asm volatile("" ::: "memory");
;     const int c = lane & 7;
; #pragma unroll
;     for (int j = 0; j < 4; ++j) { const int n = (lane >> 3) + 8 * j; const LAS float* s = scr + (8 * c) * 33 + n;
;         u32x4 o; o.x = cvt_pk_bf16(s[0 * 33] * wscale, s[1 * 33] * wscale); o.y = cvt_pk_bf16(s[2 * 33] * wscale, s[3 * 33] * wscale); o.z = cvt_pk_bf16(s[4 * 33] * wscale, s[5 * 33] * wscale); o.w = cvt_pk_bf16(s[6 * 33] * wscale, s[7 * 33] * wscale);
;         __builtin_nontemporal_store(o, (u32x4*)(WT + (size_t)(drow0 + n0 + n) * K + k0 + 8 * c)); }
;     LDS_WAIT(); asm volatile("" ::: "memory");
; __device__ __forceinline__ void prologue_a(const Args& a, LAS unsigned char* lds, int tid, int G) {
;     ...
;                 const int up = r >= 2816; if (up) r -= 2816;
;                 const int sub = r / 1408, rr = r % 1408, kb = rr / 88, nb = rr % 88, n0 = nb * 32;
;                 const float* W = a.in[up ? I_WU : I_WG] + (size_t)(l * 2 + sub) * DM * DFF;
;                 bf16_t* WT = (bf16_t*)(ws + WS_WGU) + (size_t)(l * 2 + sub) * NGU * DM;
;                 transpose_item(W, DFF, kb * 64, n0, WT, DM, 256 * (n0 >> 7) + (up ? 128 : 0) + (n0 & 127) - n0, scr, lane, up ? (1.0f / LOG2E) : LOG2E);
	ds_write2_b32 v118, v98, v99 offset0:8 offset1:74
	s_waitcnt vmcnt(8)
	ds_write2_b32 v118, v100, v101 offset0:140 offset1:206
	v_add_u32_e32 v19, 0x840, v19
	s_waitcnt vmcnt(6)
	ds_write2_b32 v19, v102, v103 offset1:66
	s_waitcnt vmcnt(4)
	ds_write2_b32 v19, v104, v105 offset0:132 offset1:198
	v_add_u32_e32 v118, 0x400, v19
	s_waitcnt vmcnt(2)
	ds_write2_b32 v118, v106, v107 offset0:8 offset1:74
	s_waitcnt vmcnt(0)
	ds_write2_b32 v118, v108, v109 offset0:140 offset1:206
	v_add_u32_e32 v19, 0x840, v19
	s_waitcnt lgkmcnt(0)
	ds_read2_b32 v[78:79], v40 offset1:33
	ds_read2_b32 v[80:81], v40 offset0:66 offset1:99
	ds_read2_b32 v[82:83], v40 offset0:132 offset1:165
	ds_read2_b32 v[84:85], v40 offset0:198 offset1:231
	ds_read2_b32 v[86:87], v40 offset0:8 offset1:41
	ds_read2_b32 v[88:89], v40 offset0:74 offset1:107
	ds_read2_b32 v[90:91], v40 offset0:140 offset1:173
	ds_read2_b32 v[92:93], v40 offset0:206 offset1:239
	ds_read2_b32 v[94:95], v40 offset0:16 offset1:49
	ds_read2_b32 v[96:97], v40 offset0:82 offset1:115
	ds_read2_b32 v[98:99], v40 offset0:148 offset1:181
	ds_read2_b32 v[100:101], v40 offset0:214 offset1:247
	ds_read2_b32 v[102:103], v40 offset0:24 offset1:57
	ds_read2_b32 v[104:105], v40 offset0:90 offset1:123
	ds_read2_b32 v[106:107], v40 offset0:156 offset1:189
	ds_read2_b32 v[108:109], v40 offset0:222 offset1:255
	s_waitcnt lgkmcnt(0)
	v_mul_f32_e32 v78, v60, v78
	v_mul_f32_e32 v79, v60, v79
	v_cvt_pk_bf16_f32 v120, v78, v79
	v_mul_f32_e32 v80, v60, v80
	v_mul_f32_e32 v81, v60, v81
	v_cvt_pk_bf16_f32 v121, v80, v81
	v_mul_f32_e32 v82, v60, v82
	v_mul_f32_e32 v83, v60, v83
	v_cvt_pk_bf16_f32 v122, v82, v83
	v_mul_f32_e32 v84, v60, v84
	v_mul_f32_e32 v85, v60, v85
	v_cvt_pk_bf16_f32 v123, v84, v85
	v_mul_f32_e32 v86, v60, v86
	v_mul_f32_e32 v87, v60, v87
	v_cvt_pk_bf16_f32 v124, v86, v87
	v_mul_f32_e32 v88, v60, v88
	v_mul_f32_e32 v89, v60, v89
	v_cvt_pk_bf16_f32 v125, v88, v89
	v_mul_f32_e32 v90, v60, v90
	v_mul_f32_e32 v91, v60, v91
	v_cvt_pk_bf16_f32 v126, v90, v91
	v_mul_f32_e32 v92, v60, v92
	v_mul_f32_e32 v93, v60, v93
	v_cvt_pk_bf16_f32 v127, v92, v93
	v_mul_f32_e32 v94, v60, v94
	v_mul_f32_e32 v95, v60, v95
	v_cvt_pk_bf16_f32 v128, v94, v95
	v_mul_f32_e32 v96, v60, v96
	v_mul_f32_e32 v97, v60, v97
	v_cvt_pk_bf16_f32 v129, v96, v97
	v_mul_f32_e32 v98, v60, v98
	v_mul_f32_e32 v99, v60, v99
	v_cvt_pk_bf16_f32 v130, v98, v99
	v_mul_f32_e32 v100, v60, v100
	v_mul_f32_e32 v101, v60, v101
	v_cvt_pk_bf16_f32 v131, v100, v101
	v_mul_f32_e32 v102, v60, v102
	v_mul_f32_e32 v103, v60, v103
	v_cvt_pk_bf16_f32 v132, v102, v103
	v_mul_f32_e32 v104, v60, v104
	v_mul_f32_e32 v105, v60, v105
	v_cvt_pk_bf16_f32 v133, v104, v105
	v_mul_f32_e32 v106, v60, v106
	v_mul_f32_e32 v107, v60, v107
	v_cvt_pk_bf16_f32 v134, v106, v107
	v_mul_f32_e32 v108, v60, v108
	v_mul_f32_e32 v109, v60, v109
	v_cvt_pk_bf16_f32 v135, v108, v109
	v_lshlrev_b32_sdwa v26, v200, sext(v0) dst_sel:DWORD dst_unused:UNUSED_PAD src0_sel:DWORD src1_sel:WORD_0
	v_and_b32_e32 v27, 0x60, v18
	v_and_b32_e32 v26, 0xffffff00, v26
	v_or3_b32 v28, v26, v61, v27
	v_lshl_add_u64 v[18:19], s[24:25], 0, v[20:21]
	v_lshlrev_b32_e32 v0, 1, v2
	v_lshl_add_u64 v[16:17], v[16:17], 1, v[18:19]
	v_lshl_add_u64 v[26:27], v[16:17], 0, v[0:1]
	v_or_b32_e32 v16, v28, v39
	v_ashrrev_i32_e32 v17, 31, v16
	v_lshlrev_b64 v[16:17], 11, v[16:17]
	v_lshl_add_u64 v[16:17], v[26:27], 0, v[16:17]
	global_store_dwordx4 v[16:17], v[120:123], off nt
	v_or_b32_e32 v22, v28, v41
	v_ashrrev_i32_e32 v23, 31, v22
	v_lshlrev_b64 v[22:23], 11, v[22:23]
	v_lshl_add_u64 v[22:23], v[26:27], 0, v[22:23]
	global_store_dwordx4 v[22:23], v[124:127], off nt
	v_or_b32_e32 v22, v28, v42
	v_ashrrev_i32_e32 v23, 31, v22
	v_lshlrev_b64 v[22:23], 11, v[22:23]
	v_lshl_add_u64 v[22:23], v[26:27], 0, v[22:23]
	global_store_dwordx4 v[22:23], v[128:131], off nt
	v_or_b32_e32 v22, v28, v43
	v_ashrrev_i32_e32 v23, 31, v22
	v_lshlrev_b64 v[22:23], 11, v[22:23]
	v_lshl_add_u64 v[20:21], v[26:27], 0, v[22:23]
	global_store_dwordx4 v[20:21], v[132:135], off nt
	s_waitcnt lgkmcnt(0)
	s_branch .LBB0_29
